# FFN1 SwiGLU epilogue: write-through (sc1) act stores (never waited on inside that epilogue; shortens the L2 flush at the phase barrier); on top of v50
# speedup vs baseline: 1.0064x; 1.0008x over previous
.LBB0_1158:
	s_ashr_i32 s13, s1, 4
	s_lshl_b32 s1, s1, 8
	v_mbcnt_lo_u32_b32 v50, -1, 0
	v_mbcnt_hi_u32_b32 v50, -1, v50
	s_add_i32 s1, s1, s72
	v_and_or_b32 v146, v50, 15, s1
	s_lshl_b32 s1, s0, 8
	v_lshrrev_b32_e32 v50, 1, v50
	s_or_b32 s1, s1, s82
	v_and_b32_e32 v154, 24, v50
	s_lshl_b32 s0, s0, 7
	v_or_b32_e32 v50, s1, v154
	s_or_b32 s0, s0, s82
	s_mul_hi_i32 s1, s13, 0xb000
	s_mul_i32 s13, s13, 0xb000
	s_add_u32 s20, s38, s13
	s_addc_u32 s21, s39, s1
	v_ashrrev_i32_e32 v51, 31, v50
	v_ashrrev_i32_e32 v147, 31, v146
	v_lshl_add_u64 v[50:51], v[50:51], 2, s[20:21]
	v_lshl_add_u64 v[152:153], v[146:147], 3, s[8:9]
	flat_load_dwordx4 v[66:69], v[50:51]
	flat_load_dwordx4 v[54:57], v[50:51] offset:16
	flat_load_dwordx4 v[62:65], v[50:51] offset:512
	s_nop 0
	flat_load_dwordx4 v[50:53], v[50:51] offset:528
	s_mov_b32 s20, 0x3fb8aa3b
	global_load_dwordx2 v[162:163], v[152:153], off
	global_load_dwordx2 v[184:185], v[152:153], off offset:128
	global_load_dwordx2 v[186:187], v[152:153], off offset:256
	global_load_dwordx2 v[188:189], v[152:153], off offset:384
	global_load_dwordx2 v[168:169], v[152:153], off offset:1024
	global_load_dwordx2 v[192:193], v[152:153], off offset:1152
	global_load_dwordx2 v[194:195], v[152:153], off offset:1280
	global_load_dwordx2 v[196:197], v[152:153], off offset:1408
	s_movk_i32 s13, 0x2c00
	s_waitcnt vmcnt(0) lgkmcnt(0)
	v_pk_mul_f32 v[148:149], v[68:69], s[20:21] op_sel_hi:[1,0]
	v_pk_mul_f32 v[150:151], v[66:67], s[20:21] op_sel_hi:[1,0]
	v_xor_b32_e32 v147, v162, v163
	v_ashrrev_i32_e32 v147, 31, v147
	v_ffbh_i32_e32 v155, v163
	v_add_u32_e32 v147, 32, v147
	v_add_u32_e32 v155, -1, v155
	v_min_u32_e32 v147, v155, v147
	v_lshlrev_b64 v[162:163], v147, v[162:163]
	v_min_u32_e32 v155, 1, v162
	v_or_b32_e32 v155, v163, v155
	v_mov_b64_e32 v[162:163], v[184:185]
	v_cvt_f32_i32_e32 v155, v155
	v_sub_u32_e32 v147, 32, v147
	v_ldexp_f32 v147, v155, v147
	v_mul_f32_e32 v167, 0x35800000, v147
	v_fmamk_f32 v167, v167, 0x3a000000, v180
	v_cmp_gt_f32_e32 vcc, s73, v167
	v_mul_f32_e32 v170, 0x4b800000, v167
	v_xor_b32_e32 v147, v162, v163
	v_ashrrev_i32_e32 v147, 31, v147
	v_ffbh_i32_e32 v155, v163
	v_add_u32_e32 v147, 32, v147
	v_add_u32_e32 v155, -1, v155
	v_min_u32_e32 v147, v155, v147
	v_lshlrev_b64 v[162:163], v147, v[162:163]
	v_min_u32_e32 v155, 1, v162
	v_or_b32_e32 v155, v163, v155
	v_mov_b64_e32 v[162:163], v[186:187]
	v_cvt_f32_i32_e32 v155, v155
	v_sub_u32_e32 v147, 32, v147
	v_cndmask_b32_e32 v167, v167, v170, vcc
	v_rsq_f32_e32 v167, v167
	v_ldexp_f32 v147, v155, v147
	v_mul_f32_e32 v165, 0x35800000, v147
	v_mul_f32_e32 v170, 0x45800000, v167
	v_cndmask_b32_e32 v170, v167, v170, vcc
	v_mul_f32_e32 v172, 0xbfb8aa3b, v170
	v_pk_fma_f32 v[174:175], v[140:141], v[172:173], v[148:149] op_sel_hi:[1,0,1] neg_lo:[0,0,1] neg_hi:[0,0,1]
	v_pk_fma_f32 v[176:177], v[138:139], v[172:173], v[150:151] op_sel_hi:[1,0,1] neg_lo:[0,0,1] neg_hi:[0,0,1]
	v_exp_f32_e32 v174, v174
	v_exp_f32_e32 v176, v176
	v_exp_f32_e32 v177, v177
	v_exp_f32_e32 v175, v175
	v_pk_fma_f32 v[134:135], v[134:135], v[170:171], v[50:51] op_sel_hi:[1,0,1]
	v_pk_fma_f32 v[136:137], v[136:137], v[170:171], v[52:53] op_sel_hi:[1,0,1]
	v_pk_add_f32 v[176:177], v[176:177], 1.0 op_sel_hi:[1,0]
	v_pk_add_f32 v[174:175], v[174:175], 1.0 op_sel_hi:[1,0]
	v_rcp_f32_e32 v176, v176
	v_rcp_f32_e32 v177, v177
	v_rcp_f32_e32 v174, v174
	v_rcp_f32_e32 v175, v175
	v_pk_fma_f32 v[138:139], v[138:139], v[170:171], v[66:67] op_sel_hi:[1,0,1]
	v_pk_fma_f32 v[142:143], v[142:143], v[170:171], v[62:63] op_sel_hi:[1,0,1]
	v_pk_fma_f32 v[140:141], v[140:141], v[170:171], v[68:69] op_sel_hi:[1,0,1]
	v_pk_fma_f32 v[144:145], v[144:145], v[170:171], v[64:65] op_sel_hi:[1,0,1]
	v_pk_mul_f32 v[138:139], v[138:139], v[142:143]
	v_pk_mul_f32 v[140:141], v[140:141], v[144:145]
	v_pk_mul_f32 v[138:139], v[138:139], v[176:177]
	v_pk_mul_f32 v[140:141], v[140:141], v[174:175]
	v_xor_b32_e32 v147, v162, v163
	v_ashrrev_i32_e32 v147, 31, v147
	v_ffbh_i32_e32 v155, v163
	v_add_u32_e32 v147, 32, v147
	v_add_u32_e32 v155, -1, v155
	v_min_u32_e32 v147, v155, v147
	v_lshlrev_b64 v[162:163], v147, v[162:163]
	v_min_u32_e32 v155, 1, v162
	v_or_b32_e32 v155, v163, v155
	v_mov_b64_e32 v[162:163], v[188:189]
	v_cvt_f32_i32_e32 v155, v155
	v_sub_u32_e32 v147, 32, v147
	v_ldexp_f32 v147, v155, v147
	v_mul_f32_e32 v164, 0x35800000, v147
	v_xor_b32_e32 v147, v162, v163
	v_ashrrev_i32_e32 v147, 31, v147
	v_ffbh_i32_e32 v155, v163
	v_add_u32_e32 v147, 32, v147
	v_add_u32_e32 v155, -1, v155
	v_min_u32_e32 v147, v155, v147
	v_lshlrev_b64 v[162:163], v147, v[162:163]
	v_min_u32_e32 v155, 1, v162
	v_or_b32_e32 v155, v163, v155
	v_cvt_f32_i32_e32 v155, v155
	v_sub_u32_e32 v147, 32, v147
	v_ldexp_f32 v147, v155, v147
	v_mul_f32_e32 v163, 0x35800000, v147
	v_xor_b32_e32 v147, v168, v169
	v_ashrrev_i32_e32 v147, 31, v147
	v_ffbh_i32_e32 v155, v169
	v_add_u32_e32 v147, 32, v147
	v_add_u32_e32 v155, -1, v155
	v_min_u32_e32 v147, v155, v147
	v_lshlrev_b64 v[168:169], v147, v[168:169]
	v_min_u32_e32 v155, 1, v168
	v_or_b32_e32 v155, v169, v155
	v_mov_b64_e32 v[168:169], v[192:193]
	v_cvt_f32_i32_e32 v155, v155
	v_sub_u32_e32 v147, 32, v147
	v_ldexp_f32 v147, v155, v147
	v_mul_f32_e32 v162, 0x35800000, v147
	v_xor_b32_e32 v147, v168, v169
	v_ashrrev_i32_e32 v147, 31, v147
	v_ffbh_i32_e32 v155, v169
	v_add_u32_e32 v147, 32, v147
	v_add_u32_e32 v155, -1, v155
	v_min_u32_e32 v147, v155, v147
	v_lshlrev_b64 v[168:169], v147, v[168:169]
	v_min_u32_e32 v155, 1, v168
	v_or_b32_e32 v155, v169, v155
	v_mov_b64_e32 v[168:169], v[194:195]
	v_cvt_f32_i32_e32 v155, v155
	v_mov_b64_e32 v[152:153], v[196:197]
	v_sub_u32_e32 v147, 32, v147
	v_ldexp_f32 v147, v155, v147
	v_mul_f32_e32 v161, 0x35800000, v147
	v_xor_b32_e32 v147, v168, v169
	v_ashrrev_i32_e32 v147, 31, v147
	v_ffbh_i32_e32 v155, v169
	v_add_u32_e32 v147, 32, v147
	v_add_u32_e32 v155, -1, v155
	v_min_u32_e32 v147, v155, v147
	v_lshlrev_b64 v[168:169], v147, v[168:169]
	v_min_u32_e32 v155, 1, v168
	v_or_b32_e32 v155, v169, v155
	v_cvt_f32_i32_e32 v155, v155
	v_sub_u32_e32 v147, 32, v147
	v_ffbh_i32_e32 v166, v153
	v_add_u32_e32 v166, -1, v166
	v_ldexp_f32 v147, v155, v147
	v_xor_b32_e32 v155, v152, v153
	v_ashrrev_i32_e32 v155, 31, v155
	v_add_u32_e32 v155, 32, v155
	v_min_u32_e32 v155, v166, v155
	v_lshlrev_b64 v[152:153], v155, v[152:153]
	v_min_u32_e32 v152, 1, v152
	v_or_b32_e32 v152, v153, v152
	v_cvt_f32_i32_e32 v152, v152
	v_sub_u32_e32 v153, 32, v155
	v_or_b32_e32 v168, s0, v154
	v_pk_mul_f32 v[154:155], v[54:55], s[20:21] op_sel_hi:[1,0]
	v_ldexp_f32 v152, v152, v153
	v_mul_f32_e32 v166, 0x35800000, v152
	v_pk_mul_f32 v[152:153], v[56:57], s[20:21] op_sel_hi:[1,0]
	v_ashrrev_i32_e32 v169, 31, v168
	v_pk_fma_f32 v[178:179], v[132:133], v[172:173], v[152:153] op_sel_hi:[1,0,1] neg_lo:[0,0,1] neg_hi:[0,0,1]
	v_pk_fma_f32 v[172:173], v[130:131], v[172:173], v[154:155] op_sel_hi:[1,0,1] neg_lo:[0,0,1] neg_hi:[0,0,1]
	v_exp_f32_e32 v178, v178
	v_exp_f32_e32 v172, v172
	v_exp_f32_e32 v173, v173
	v_exp_f32_e32 v179, v179
	v_pk_fma_f32 v[130:131], v[130:131], v[170:171], v[54:55] op_sel_hi:[1,0,1]
	v_pk_fma_f32 v[132:133], v[132:133], v[170:171], v[56:57] op_sel_hi:[1,0,1]
	v_pk_add_f32 v[172:173], v[172:173], 1.0 op_sel_hi:[1,0]
	v_pk_add_f32 v[178:179], v[178:179], 1.0 op_sel_hi:[1,0]
	v_rcp_f32_e32 v172, v172
	v_rcp_f32_e32 v173, v173
	v_rcp_f32_e32 v178, v178
	v_rcp_f32_e32 v179, v179
	v_pk_mul_f32 v[130:131], v[130:131], v[134:135]
	v_pk_mul_f32 v[132:133], v[132:133], v[136:137]
	v_pk_mul_f32 v[136:137], v[130:131], v[172:173]
	v_mov_b64_e32 v[130:131], s[10:11]
	v_pk_mul_f32 v[142:143], v[132:133], v[178:179]
	v_mad_i64_i32 v[134:135], s[0:1], v146, s13, v[130:131]
	v_lshlrev_b64 v[132:133], 1, v[168:169]
	v_lshl_add_u64 v[144:145], v[134:135], 0, v[132:133]
	v_cvt_pk_bf16_f32 v134, v138, v139
	v_cvt_pk_bf16_f32 v135, v140, v141
	v_cvt_pk_bf16_f32 v136, v136, v137
	v_cvt_pk_bf16_f32 v137, v142, v143
	flat_store_dwordx4 v[144:145], v[134:137] sc1
	v_mul_f32_e32 v147, 0x35800000, v147
	s_mov_b64 s[20:21], -1
	v_fmamk_f32 v134, v165, 0x3a000000, v180
	v_cmp_gt_f32_e32 vcc, s73, v134
	v_mul_f32_e32 v135, 0x4b800000, v134
	s_nop 0
	v_cndmask_b32_e32 v134, v134, v135, vcc
	v_rsq_f32_e32 v134, v134
	s_nop 0
	v_mul_f32_e32 v135, 0x45800000, v134
	v_cndmask_b32_e32 v134, v134, v135, vcc
	v_mul_f32_e32 v136, 0xbfb8aa3b, v134
	v_pk_fma_f32 v[138:139], v[124:125], v[136:137], v[148:149] op_sel_hi:[1,0,1] neg_lo:[0,0,1] neg_hi:[0,0,1]
	v_pk_fma_f32 v[140:141], v[122:123], v[136:137], v[150:151] op_sel_hi:[1,0,1] neg_lo:[0,0,1] neg_hi:[0,0,1]
	v_pk_fma_f32 v[142:143], v[116:117], v[136:137], v[152:153] op_sel_hi:[1,0,1] neg_lo:[0,0,1] neg_hi:[0,0,1]
	v_pk_fma_f32 v[136:137], v[114:115], v[136:137], v[154:155] op_sel_hi:[1,0,1] neg_lo:[0,0,1] neg_hi:[0,0,1]
	v_exp_f32_e32 v142, v142
	v_exp_f32_e32 v136, v136
	v_exp_f32_e32 v137, v137
	v_exp_f32_e32 v143, v143
	v_exp_f32_e32 v140, v140
	v_exp_f32_e32 v141, v141
	v_exp_f32_e32 v138, v138
	v_exp_f32_e32 v139, v139
	v_pk_add_f32 v[142:143], v[142:143], 1.0 op_sel_hi:[1,0]
	v_pk_add_f32 v[136:137], v[136:137], 1.0 op_sel_hi:[1,0]
	v_pk_add_f32 v[140:141], v[140:141], 1.0 op_sel_hi:[1,0]
	v_rcp_f32_e32 v136, v136
	v_rcp_f32_e32 v137, v137
	v_rcp_f32_e32 v142, v142
	v_rcp_f32_e32 v143, v143
	v_pk_fma_f32 v[124:125], v[124:125], v[134:135], v[68:69] op_sel_hi:[1,0,1]
	v_pk_fma_f32 v[122:123], v[122:123], v[134:135], v[66:67] op_sel_hi:[1,0,1]
	v_pk_fma_f32 v[128:129], v[128:129], v[134:135], v[64:65] op_sel_hi:[1,0,1]
	v_pk_fma_f32 v[126:127], v[126:127], v[134:135], v[62:63] op_sel_hi:[1,0,1]
	v_pk_add_f32 v[138:139], v[138:139], 1.0 op_sel_hi:[1,0]
	v_rcp_f32_e32 v140, v140
	v_rcp_f32_e32 v141, v141
	v_or_b32_e32 v135, 16, v146
	v_rcp_f32_e32 v138, v138
	v_rcp_f32_e32 v139, v139
	v_pk_fma_f32 v[116:117], v[116:117], v[134:135], v[56:57] op_sel_hi:[1,0,1]
	v_pk_fma_f32 v[114:115], v[114:115], v[134:135], v[54:55] op_sel_hi:[1,0,1]
	v_pk_fma_f32 v[120:121], v[120:121], v[134:135], v[52:53] op_sel_hi:[1,0,1]
	v_pk_fma_f32 v[118:119], v[118:119], v[134:135], v[50:51] op_sel_hi:[1,0,1]
	v_pk_mul_f32 v[116:117], v[116:117], v[120:121]
	v_pk_mul_f32 v[114:115], v[114:115], v[118:119]
	v_pk_mul_f32 v[122:123], v[122:123], v[126:127]
	v_pk_mul_f32 v[118:119], v[116:117], v[142:143]
	v_pk_mul_f32 v[116:117], v[114:115], v[136:137]
	v_mad_i64_i32 v[114:115], s[0:1], v135, s13, v[130:131]
	v_pk_mul_f32 v[124:125], v[124:125], v[128:129]
	v_pk_mul_f32 v[122:123], v[122:123], v[140:141]
	v_lshl_add_u64 v[120:121], v[114:115], 0, v[132:133]
	v_cvt_pk_bf16_f32 v114, v122, v123
	v_pk_mul_f32 v[124:125], v[124:125], v[138:139]
	s_nop 0
	v_cvt_pk_bf16_f32 v115, v124, v125
	v_cvt_pk_bf16_f32 v116, v116, v117
	v_cvt_pk_bf16_f32 v117, v118, v119
	flat_store_dwordx4 v[120:121], v[114:117] sc1
	s_nop 1
	v_fmamk_f32 v114, v164, 0x3a000000, v180
	v_cmp_gt_f32_e32 vcc, s73, v114
	v_mul_f32_e32 v115, 0x4b800000, v114
	s_nop 0
	v_cndmask_b32_e32 v114, v114, v115, vcc
	v_rsq_f32_e32 v114, v114
	s_nop 0
	v_mul_f32_e32 v115, 0x45800000, v114
	v_cndmask_b32_e32 v114, v114, v115, vcc
	v_mul_f32_e32 v116, 0xbfb8aa3b, v114
	v_pk_fma_f32 v[118:119], v[108:109], v[116:117], v[148:149] op_sel_hi:[1,0,1] neg_lo:[0,0,1] neg_hi:[0,0,1]
	v_pk_fma_f32 v[120:121], v[106:107], v[116:117], v[150:151] op_sel_hi:[1,0,1] neg_lo:[0,0,1] neg_hi:[0,0,1]
	v_pk_fma_f32 v[122:123], v[100:101], v[116:117], v[152:153] op_sel_hi:[1,0,1] neg_lo:[0,0,1] neg_hi:[0,0,1]
	v_pk_fma_f32 v[116:117], v[98:99], v[116:117], v[154:155] op_sel_hi:[1,0,1] neg_lo:[0,0,1] neg_hi:[0,0,1]
	v_exp_f32_e32 v122, v122
	v_exp_f32_e32 v116, v116
	v_exp_f32_e32 v117, v117
	v_exp_f32_e32 v123, v123
	v_exp_f32_e32 v120, v120
	v_exp_f32_e32 v121, v121
	v_exp_f32_e32 v118, v118
	v_exp_f32_e32 v119, v119
	v_pk_add_f32 v[122:123], v[122:123], 1.0 op_sel_hi:[1,0]
	v_pk_add_f32 v[116:117], v[116:117], 1.0 op_sel_hi:[1,0]
	v_pk_add_f32 v[120:121], v[120:121], 1.0 op_sel_hi:[1,0]
	v_rcp_f32_e32 v116, v116
	v_rcp_f32_e32 v117, v117
	v_rcp_f32_e32 v122, v122
	v_rcp_f32_e32 v123, v123
	v_pk_fma_f32 v[108:109], v[108:109], v[114:115], v[68:69] op_sel_hi:[1,0,1]
	v_pk_fma_f32 v[106:107], v[106:107], v[114:115], v[66:67] op_sel_hi:[1,0,1]
	v_pk_fma_f32 v[112:113], v[112:113], v[114:115], v[64:65] op_sel_hi:[1,0,1]
	v_pk_fma_f32 v[110:111], v[110:111], v[114:115], v[62:63] op_sel_hi:[1,0,1]
	v_pk_add_f32 v[118:119], v[118:119], 1.0 op_sel_hi:[1,0]
	v_rcp_f32_e32 v120, v120
	v_rcp_f32_e32 v121, v121
	v_or_b32_e32 v115, 32, v146
	v_rcp_f32_e32 v118, v118
	v_rcp_f32_e32 v119, v119
	v_pk_fma_f32 v[100:101], v[100:101], v[114:115], v[56:57] op_sel_hi:[1,0,1]
	v_pk_fma_f32 v[98:99], v[98:99], v[114:115], v[54:55] op_sel_hi:[1,0,1]
	v_pk_fma_f32 v[104:105], v[104:105], v[114:115], v[52:53] op_sel_hi:[1,0,1]
	v_pk_fma_f32 v[102:103], v[102:103], v[114:115], v[50:51] op_sel_hi:[1,0,1]
	v_pk_mul_f32 v[100:101], v[100:101], v[104:105]
	v_pk_mul_f32 v[98:99], v[98:99], v[102:103]
	v_pk_mul_f32 v[106:107], v[106:107], v[110:111]
	v_pk_mul_f32 v[102:103], v[100:101], v[122:123]
	v_pk_mul_f32 v[100:101], v[98:99], v[116:117]
	v_mad_i64_i32 v[98:99], s[0:1], v115, s13, v[130:131]
	v_pk_mul_f32 v[108:109], v[108:109], v[112:113]
	v_pk_mul_f32 v[106:107], v[106:107], v[120:121]
	v_lshl_add_u64 v[104:105], v[98:99], 0, v[132:133]
	v_cvt_pk_bf16_f32 v98, v106, v107
	v_pk_mul_f32 v[108:109], v[108:109], v[118:119]
	s_nop 0
	v_cvt_pk_bf16_f32 v99, v108, v109
	v_cvt_pk_bf16_f32 v100, v100, v101
	v_cvt_pk_bf16_f32 v101, v102, v103
	flat_store_dwordx4 v[104:105], v[98:101] sc1
	s_nop 1
	v_fmamk_f32 v98, v163, 0x3a000000, v180
	v_cmp_gt_f32_e32 vcc, s73, v98
	v_mul_f32_e32 v99, 0x4b800000, v98
	s_nop 0
	v_cndmask_b32_e32 v98, v98, v99, vcc
	v_rsq_f32_e32 v98, v98
	s_nop 0
	v_mul_f32_e32 v99, 0x45800000, v98
	v_cndmask_b32_e32 v98, v98, v99, vcc
	v_mul_f32_e32 v100, 0xbfb8aa3b, v98
	v_pk_fma_f32 v[102:103], v[92:93], v[100:101], v[148:149] op_sel_hi:[1,0,1] neg_lo:[0,0,1] neg_hi:[0,0,1]
	v_pk_fma_f32 v[104:105], v[90:91], v[100:101], v[150:151] op_sel_hi:[1,0,1] neg_lo:[0,0,1] neg_hi:[0,0,1]
	v_pk_fma_f32 v[106:107], v[84:85], v[100:101], v[152:153] op_sel_hi:[1,0,1] neg_lo:[0,0,1] neg_hi:[0,0,1]
	v_pk_fma_f32 v[100:101], v[82:83], v[100:101], v[154:155] op_sel_hi:[1,0,1] neg_lo:[0,0,1] neg_hi:[0,0,1]
	v_exp_f32_e32 v106, v106
	v_exp_f32_e32 v100, v100
	v_exp_f32_e32 v101, v101
	v_exp_f32_e32 v107, v107
	v_exp_f32_e32 v104, v104
	v_exp_f32_e32 v105, v105
	v_exp_f32_e32 v102, v102
	v_exp_f32_e32 v103, v103
	v_pk_add_f32 v[106:107], v[106:107], 1.0 op_sel_hi:[1,0]
	v_pk_add_f32 v[100:101], v[100:101], 1.0 op_sel_hi:[1,0]
	v_pk_add_f32 v[104:105], v[104:105], 1.0 op_sel_hi:[1,0]
	v_rcp_f32_e32 v100, v100
	v_rcp_f32_e32 v101, v101
	v_rcp_f32_e32 v106, v106
	v_rcp_f32_e32 v107, v107
	v_pk_fma_f32 v[92:93], v[92:93], v[98:99], v[68:69] op_sel_hi:[1,0,1]
	v_pk_fma_f32 v[90:91], v[90:91], v[98:99], v[66:67] op_sel_hi:[1,0,1]
	v_pk_fma_f32 v[96:97], v[96:97], v[98:99], v[64:65] op_sel_hi:[1,0,1]
	v_pk_fma_f32 v[94:95], v[94:95], v[98:99], v[62:63] op_sel_hi:[1,0,1]
	v_pk_add_f32 v[102:103], v[102:103], 1.0 op_sel_hi:[1,0]
	v_rcp_f32_e32 v104, v104
	v_rcp_f32_e32 v105, v105
	v_or_b32_e32 v99, 48, v146
	v_rcp_f32_e32 v102, v102
	v_rcp_f32_e32 v103, v103
	v_pk_fma_f32 v[84:85], v[84:85], v[98:99], v[56:57] op_sel_hi:[1,0,1]
	v_pk_fma_f32 v[82:83], v[82:83], v[98:99], v[54:55] op_sel_hi:[1,0,1]
	v_pk_fma_f32 v[88:89], v[88:89], v[98:99], v[52:53] op_sel_hi:[1,0,1]
	v_pk_fma_f32 v[86:87], v[86:87], v[98:99], v[50:51] op_sel_hi:[1,0,1]
	v_pk_mul_f32 v[84:85], v[84:85], v[88:89]
	v_pk_mul_f32 v[82:83], v[82:83], v[86:87]
	v_pk_mul_f32 v[90:91], v[90:91], v[94:95]
	v_pk_mul_f32 v[86:87], v[84:85], v[106:107]
	v_pk_mul_f32 v[84:85], v[82:83], v[100:101]
	v_mad_i64_i32 v[82:83], s[0:1], v99, s13, v[130:131]
	v_pk_mul_f32 v[92:93], v[92:93], v[96:97]
	v_pk_mul_f32 v[90:91], v[90:91], v[104:105]
	v_lshl_add_u64 v[88:89], v[82:83], 0, v[132:133]
	v_cvt_pk_bf16_f32 v82, v90, v91
	v_pk_mul_f32 v[92:93], v[92:93], v[102:103]
	s_nop 0
	v_cvt_pk_bf16_f32 v83, v92, v93
	v_cvt_pk_bf16_f32 v84, v84, v85
	v_cvt_pk_bf16_f32 v85, v86, v87
	flat_store_dwordx4 v[88:89], v[82:85] sc1
	s_nop 1
	v_fmamk_f32 v82, v162, 0x3a000000, v180
	v_cmp_gt_f32_e32 vcc, s73, v82
	v_mul_f32_e32 v84, 0x4b800000, v82
	v_add_u32_e32 v83, 0x80, v146
	v_cndmask_b32_e32 v82, v82, v84, vcc
	v_rsq_f32_e32 v82, v82
	s_nop 0
	v_mul_f32_e32 v84, 0x45800000, v82
	v_cndmask_b32_e32 v82, v82, v84, vcc
	v_mul_f32_e32 v84, 0xbfb8aa3b, v82
	v_pk_fma_f32 v[86:87], v[76:77], v[84:85], v[148:149] op_sel_hi:[1,0,1] neg_lo:[0,0,1] neg_hi:[0,0,1]
	v_pk_fma_f32 v[88:89], v[74:75], v[84:85], v[150:151] op_sel_hi:[1,0,1] neg_lo:[0,0,1] neg_hi:[0,0,1]
	v_pk_fma_f32 v[90:91], v[60:61], v[84:85], v[152:153] op_sel_hi:[1,0,1] neg_lo:[0,0,1] neg_hi:[0,0,1]
	v_pk_fma_f32 v[84:85], v[58:59], v[84:85], v[154:155] op_sel_hi:[1,0,1] neg_lo:[0,0,1] neg_hi:[0,0,1]
	v_exp_f32_e32 v90, v90
	v_exp_f32_e32 v84, v84
	v_exp_f32_e32 v85, v85
	v_exp_f32_e32 v91, v91
	v_exp_f32_e32 v88, v88
	v_exp_f32_e32 v89, v89
	v_exp_f32_e32 v86, v86
	v_exp_f32_e32 v87, v87
	v_pk_add_f32 v[90:91], v[90:91], 1.0 op_sel_hi:[1,0]
	v_pk_add_f32 v[84:85], v[84:85], 1.0 op_sel_hi:[1,0]
	v_pk_add_f32 v[88:89], v[88:89], 1.0 op_sel_hi:[1,0]
	v_rcp_f32_e32 v84, v84
	v_rcp_f32_e32 v85, v85
	v_rcp_f32_e32 v90, v90
	v_rcp_f32_e32 v91, v91
	v_pk_add_f32 v[86:87], v[86:87], 1.0 op_sel_hi:[1,0]
	v_rcp_f32_e32 v88, v88
	v_rcp_f32_e32 v89, v89
	v_rcp_f32_e32 v86, v86
	v_rcp_f32_e32 v87, v87
	v_pk_fma_f32 v[60:61], v[60:61], v[82:83], v[56:57] op_sel_hi:[1,0,1]
	v_pk_fma_f32 v[58:59], v[58:59], v[82:83], v[54:55] op_sel_hi:[1,0,1]
	v_pk_fma_f32 v[72:73], v[72:73], v[82:83], v[52:53] op_sel_hi:[1,0,1]
	v_pk_fma_f32 v[70:71], v[70:71], v[82:83], v[50:51] op_sel_hi:[1,0,1]
	v_pk_fma_f32 v[74:75], v[74:75], v[82:83], v[66:67] op_sel_hi:[1,0,1]
	v_pk_fma_f32 v[78:79], v[78:79], v[82:83], v[62:63] op_sel_hi:[1,0,1]
	v_pk_mul_f32 v[58:59], v[58:59], v[70:71]
	v_pk_mul_f32 v[60:61], v[60:61], v[72:73]
	v_pk_fma_f32 v[76:77], v[76:77], v[82:83], v[68:69] op_sel_hi:[1,0,1]
	v_pk_fma_f32 v[80:81], v[80:81], v[82:83], v[64:65] op_sel_hi:[1,0,1]
	v_pk_mul_f32 v[74:75], v[74:75], v[78:79]
	v_pk_mul_f32 v[70:71], v[60:61], v[90:91]
	v_pk_mul_f32 v[60:61], v[58:59], v[84:85]
	v_mad_i64_i32 v[58:59], s[0:1], v83, s13, v[130:131]
	v_pk_mul_f32 v[76:77], v[76:77], v[80:81]
	v_pk_mul_f32 v[74:75], v[74:75], v[88:89]
	v_lshl_add_u64 v[72:73], v[58:59], 0, v[132:133]
	v_cvt_pk_bf16_f32 v58, v74, v75
	v_pk_mul_f32 v[76:77], v[76:77], v[86:87]
	s_nop 0
	v_cvt_pk_bf16_f32 v59, v76, v77
	v_cvt_pk_bf16_f32 v60, v60, v61
	v_cvt_pk_bf16_f32 v61, v70, v71
	flat_store_dwordx4 v[72:73], v[58:61] sc1
	s_nop 1
	v_fmamk_f32 v58, v161, 0x3a000000, v180
	v_cmp_gt_f32_e32 vcc, s73, v58
	v_mul_f32_e32 v59, 0x4b800000, v58
	s_nop 0
	v_cndmask_b32_e32 v58, v58, v59, vcc
	v_rsq_f32_e32 v58, v58
	s_nop 0
	v_mul_f32_e32 v59, 0x45800000, v58
	v_cndmask_b32_e32 v58, v58, v59, vcc
	v_mul_f32_e32 v60, 0xbfb8aa3b, v58
	v_pk_fma_f32 v[70:71], v[44:45], v[60:61], v[148:149] op_sel_hi:[1,0,1] neg_lo:[0,0,1] neg_hi:[0,0,1]
	v_pk_fma_f32 v[72:73], v[42:43], v[60:61], v[150:151] op_sel_hi:[1,0,1] neg_lo:[0,0,1] neg_hi:[0,0,1]
	v_pk_fma_f32 v[74:75], v[36:37], v[60:61], v[152:153] op_sel_hi:[1,0,1] neg_lo:[0,0,1] neg_hi:[0,0,1]
	v_pk_fma_f32 v[60:61], v[34:35], v[60:61], v[154:155] op_sel_hi:[1,0,1] neg_lo:[0,0,1] neg_hi:[0,0,1]
	v_exp_f32_e32 v74, v74
	v_exp_f32_e32 v60, v60
	v_exp_f32_e32 v61, v61
	v_exp_f32_e32 v75, v75
	v_exp_f32_e32 v72, v72
	v_exp_f32_e32 v73, v73
	v_exp_f32_e32 v70, v70
	v_exp_f32_e32 v71, v71
	v_pk_add_f32 v[74:75], v[74:75], 1.0 op_sel_hi:[1,0]
	v_pk_add_f32 v[60:61], v[60:61], 1.0 op_sel_hi:[1,0]
	v_pk_add_f32 v[72:73], v[72:73], 1.0 op_sel_hi:[1,0]
	v_rcp_f32_e32 v60, v60
	v_rcp_f32_e32 v61, v61
	v_rcp_f32_e32 v74, v74
	v_rcp_f32_e32 v75, v75
	v_pk_fma_f32 v[44:45], v[44:45], v[58:59], v[68:69] op_sel_hi:[1,0,1]
	v_pk_fma_f32 v[42:43], v[42:43], v[58:59], v[66:67] op_sel_hi:[1,0,1]
	v_pk_fma_f32 v[48:49], v[48:49], v[58:59], v[64:65] op_sel_hi:[1,0,1]
	v_pk_fma_f32 v[46:47], v[46:47], v[58:59], v[62:63] op_sel_hi:[1,0,1]
	v_pk_add_f32 v[70:71], v[70:71], 1.0 op_sel_hi:[1,0]
	v_rcp_f32_e32 v72, v72
	v_rcp_f32_e32 v73, v73
	v_add_u32_e32 v59, 0x90, v146
	v_rcp_f32_e32 v70, v70
	v_rcp_f32_e32 v71, v71
	v_pk_fma_f32 v[36:37], v[36:37], v[58:59], v[56:57] op_sel_hi:[1,0,1]
	v_pk_fma_f32 v[34:35], v[34:35], v[58:59], v[54:55] op_sel_hi:[1,0,1]
	v_pk_fma_f32 v[40:41], v[40:41], v[58:59], v[52:53] op_sel_hi:[1,0,1]
	v_pk_fma_f32 v[38:39], v[38:39], v[58:59], v[50:51] op_sel_hi:[1,0,1]
	v_pk_mul_f32 v[36:37], v[36:37], v[40:41]
	v_pk_mul_f32 v[34:35], v[34:35], v[38:39]
	v_pk_mul_f32 v[42:43], v[42:43], v[46:47]
	v_pk_mul_f32 v[38:39], v[36:37], v[74:75]
	v_pk_mul_f32 v[36:37], v[34:35], v[60:61]
	v_mad_i64_i32 v[34:35], s[0:1], v59, s13, v[130:131]
	v_pk_mul_f32 v[44:45], v[44:45], v[48:49]
	v_pk_mul_f32 v[42:43], v[42:43], v[72:73]
	v_lshl_add_u64 v[40:41], v[34:35], 0, v[132:133]
	v_cvt_pk_bf16_f32 v34, v42, v43
	v_pk_mul_f32 v[44:45], v[44:45], v[70:71]
	s_nop 0
	v_cvt_pk_bf16_f32 v35, v44, v45
	v_cvt_pk_bf16_f32 v36, v36, v37
	v_cvt_pk_bf16_f32 v37, v38, v39
	flat_store_dwordx4 v[40:41], v[34:37] sc1
	s_nop 1
	v_fmamk_f32 v34, v147, 0x3a000000, v180
	v_cmp_gt_f32_e32 vcc, s73, v34
	v_mul_f32_e32 v35, 0x4b800000, v34
	s_nop 0
	v_cndmask_b32_e32 v34, v34, v35, vcc
	v_rsq_f32_e32 v34, v34
	s_nop 0
	v_mul_f32_e32 v35, 0x45800000, v34
	v_cndmask_b32_e32 v34, v34, v35, vcc
	v_mul_f32_e32 v36, 0xbfb8aa3b, v34
	v_pk_fma_f32 v[38:39], v[28:29], v[36:37], v[148:149] op_sel_hi:[1,0,1] neg_lo:[0,0,1] neg_hi:[0,0,1]
	v_pk_fma_f32 v[40:41], v[26:27], v[36:37], v[150:151] op_sel_hi:[1,0,1] neg_lo:[0,0,1] neg_hi:[0,0,1]
	v_pk_fma_f32 v[42:43], v[20:21], v[36:37], v[152:153] op_sel_hi:[1,0,1] neg_lo:[0,0,1] neg_hi:[0,0,1]
	v_pk_fma_f32 v[36:37], v[18:19], v[36:37], v[154:155] op_sel_hi:[1,0,1] neg_lo:[0,0,1] neg_hi:[0,0,1]
	v_exp_f32_e32 v42, v42
	v_exp_f32_e32 v36, v36
	v_exp_f32_e32 v37, v37
	v_exp_f32_e32 v43, v43
	v_exp_f32_e32 v40, v40
	v_exp_f32_e32 v41, v41
	v_exp_f32_e32 v38, v38
	v_exp_f32_e32 v39, v39
	v_pk_add_f32 v[42:43], v[42:43], 1.0 op_sel_hi:[1,0]
	v_pk_add_f32 v[36:37], v[36:37], 1.0 op_sel_hi:[1,0]
	v_pk_add_f32 v[40:41], v[40:41], 1.0 op_sel_hi:[1,0]
	v_rcp_f32_e32 v36, v36
	v_rcp_f32_e32 v37, v37
	v_rcp_f32_e32 v42, v42
	v_rcp_f32_e32 v43, v43
	v_pk_fma_f32 v[28:29], v[28:29], v[34:35], v[68:69] op_sel_hi:[1,0,1]
	v_pk_fma_f32 v[26:27], v[26:27], v[34:35], v[66:67] op_sel_hi:[1,0,1]
	v_pk_fma_f32 v[32:33], v[32:33], v[34:35], v[64:65] op_sel_hi:[1,0,1]
	v_pk_fma_f32 v[30:31], v[30:31], v[34:35], v[62:63] op_sel_hi:[1,0,1]
	v_pk_add_f32 v[38:39], v[38:39], 1.0 op_sel_hi:[1,0]
	v_rcp_f32_e32 v40, v40
	v_rcp_f32_e32 v41, v41
	v_add_u32_e32 v35, 0xa0, v146
	v_rcp_f32_e32 v38, v38
	v_rcp_f32_e32 v39, v39
	v_pk_fma_f32 v[20:21], v[20:21], v[34:35], v[56:57] op_sel_hi:[1,0,1]
	v_pk_fma_f32 v[18:19], v[18:19], v[34:35], v[54:55] op_sel_hi:[1,0,1]
	v_pk_fma_f32 v[24:25], v[24:25], v[34:35], v[52:53] op_sel_hi:[1,0,1]
	v_pk_fma_f32 v[22:23], v[22:23], v[34:35], v[50:51] op_sel_hi:[1,0,1]
	v_pk_mul_f32 v[20:21], v[20:21], v[24:25]
	v_pk_mul_f32 v[18:19], v[18:19], v[22:23]
	v_pk_mul_f32 v[26:27], v[26:27], v[30:31]
	v_pk_mul_f32 v[22:23], v[20:21], v[42:43]
	v_pk_mul_f32 v[20:21], v[18:19], v[36:37]
	v_mad_i64_i32 v[18:19], s[0:1], v35, s13, v[130:131]
	v_pk_mul_f32 v[28:29], v[28:29], v[32:33]
	v_pk_mul_f32 v[26:27], v[26:27], v[40:41]
	v_lshl_add_u64 v[24:25], v[18:19], 0, v[132:133]
	v_cvt_pk_bf16_f32 v18, v26, v27
	v_pk_mul_f32 v[28:29], v[28:29], v[38:39]
	s_nop 0
	v_cvt_pk_bf16_f32 v19, v28, v29
	v_cvt_pk_bf16_f32 v20, v20, v21
	v_cvt_pk_bf16_f32 v21, v22, v23
	flat_store_dwordx4 v[24:25], v[18:21] sc1
	s_nop 1
	v_fmamk_f32 v18, v166, 0x3a000000, v180
	v_cmp_gt_f32_e32 vcc, s73, v18
	v_mul_f32_e32 v19, 0x4b800000, v18
	s_nop 0
	v_cndmask_b32_e32 v18, v18, v19, vcc
	v_rsq_f32_e32 v18, v18
	s_nop 0
	v_mul_f32_e32 v19, 0x45800000, v18
	v_cndmask_b32_e32 v18, v18, v19, vcc
	v_mul_f32_e32 v20, 0xbfb8aa3b, v18
	v_pk_fma_f32 v[22:23], v[12:13], v[20:21], v[148:149] op_sel_hi:[1,0,1] neg_lo:[0,0,1] neg_hi:[0,0,1]
	v_pk_fma_f32 v[24:25], v[10:11], v[20:21], v[150:151] op_sel_hi:[1,0,1] neg_lo:[0,0,1] neg_hi:[0,0,1]
	v_pk_fma_f32 v[26:27], v[4:5], v[20:21], v[152:153] op_sel_hi:[1,0,1] neg_lo:[0,0,1] neg_hi:[0,0,1]
	v_pk_fma_f32 v[20:21], v[2:3], v[20:21], v[154:155] op_sel_hi:[1,0,1] neg_lo:[0,0,1] neg_hi:[0,0,1]
	v_exp_f32_e32 v26, v26
	v_exp_f32_e32 v20, v20
	v_exp_f32_e32 v21, v21
	v_exp_f32_e32 v27, v27
	v_exp_f32_e32 v24, v24
	v_exp_f32_e32 v25, v25
	v_exp_f32_e32 v22, v22
	v_exp_f32_e32 v23, v23
	v_pk_add_f32 v[26:27], v[26:27], 1.0 op_sel_hi:[1,0]
	v_pk_add_f32 v[20:21], v[20:21], 1.0 op_sel_hi:[1,0]
	v_rcp_f32_e32 v26, v26
	v_rcp_f32_e32 v20, v20
	v_rcp_f32_e32 v21, v21
	v_rcp_f32_e32 v27, v27
	v_pk_fma_f32 v[12:13], v[12:13], v[18:19], v[68:69] op_sel_hi:[1,0,1]
	v_pk_fma_f32 v[10:11], v[10:11], v[18:19], v[66:67] op_sel_hi:[1,0,1]
	v_pk_fma_f32 v[16:17], v[16:17], v[18:19], v[64:65] op_sel_hi:[1,0,1]
	v_pk_fma_f32 v[14:15], v[14:15], v[18:19], v[62:63] op_sel_hi:[1,0,1]
	v_pk_add_f32 v[22:23], v[22:23], 1.0 op_sel_hi:[1,0]
	v_pk_add_f32 v[24:25], v[24:25], 1.0 op_sel_hi:[1,0]
	v_add_u32_e32 v19, 0xb0, v146
	v_rcp_f32_e32 v24, v24
	v_rcp_f32_e32 v25, v25
	v_rcp_f32_e32 v22, v22
	v_rcp_f32_e32 v23, v23
	v_pk_fma_f32 v[4:5], v[4:5], v[18:19], v[56:57] op_sel_hi:[1,0,1]
	v_pk_fma_f32 v[2:3], v[2:3], v[18:19], v[54:55] op_sel_hi:[1,0,1]
	v_pk_fma_f32 v[8:9], v[8:9], v[18:19], v[52:53] op_sel_hi:[1,0,1]
	v_pk_fma_f32 v[6:7], v[6:7], v[18:19], v[50:51] op_sel_hi:[1,0,1]
	v_pk_mul_f32 v[4:5], v[4:5], v[8:9]
	v_pk_mul_f32 v[2:3], v[2:3], v[6:7]
	v_pk_mul_f32 v[6:7], v[4:5], v[26:27]
	v_pk_mul_f32 v[4:5], v[2:3], v[20:21]
	v_mad_i64_i32 v[2:3], s[0:1], v19, s13, v[130:131]
	v_pk_mul_f32 v[10:11], v[10:11], v[14:15]
	v_pk_mul_f32 v[12:13], v[12:13], v[16:17]
	v_lshl_add_u64 v[8:9], v[2:3], 0, v[132:133]
	s_andn2_b64 vcc, exec, s[6:7]
	v_pk_mul_f32 v[12:13], v[12:13], v[22:23]
	v_pk_mul_f32 v[10:11], v[10:11], v[24:25]
	s_nop 0
	v_cvt_pk_bf16_f32 v2, v10, v11
	v_cvt_pk_bf16_f32 v3, v12, v13
	v_cvt_pk_bf16_f32 v4, v4, v5
	v_cvt_pk_bf16_f32 v5, v6, v7
	flat_store_dwordx4 v[8:9], v[2:5] sc1
	s_cbranch_vccnz .LBB0_1145
	s_and_b64 vcc, exec, s[2:3]
	s_cbranch_vccnz .LBB0_1144
	s_barrier
	s_branch .LBB0_1144
